# output GEMM LayerNorm statistics exchange: L1 invalidate after the panel-counter poll removed (the statistics words are read with sc1 loads)
# speedup vs baseline: 1.0016x; 1.0016x over previous
;     __device__ __forceinline__ bool run(const f32x4 (&v)[2][2][4][2], const Unit& u, int wr, int wc, int fr, int fq, PG8_LAS unsigned char* lds, int wid, int lane) const {
;     ...
;             bool dead = false; const unsigned long long t0 = __builtin_amdgcn_s_memrealtime(); const unsigned want = 8u * (unsigned)ntn;
;             for (;;) {
;                 if ((unsigned)__builtin_amdgcn_readfirstlane(__hip_atomic_load(cnt + 64 * u.pm, __ATOMIC_RELAXED, __HIP_MEMORY_SCOPE_AGENT)) >= want) break;
;                 if (__builtin_amdgcn_s_memrealtime() - t0 > 2000000ull) {
;                     if (lane == 0) { unsigned expect = 0u; __hip_atomic_compare_exchange_strong(tmo + 1, &expect, code | (unsigned)(u.pm & 0xff), __ATOMIC_RELAXED, __ATOMIC_RELAXED, __HIP_MEMORY_SCOPE_AGENT);
;                                      __hip_atomic_store(tmo, 1u, __ATOMIC_RELAXED, __HIP_MEMORY_SCOPE_AGENT); }
;                     dead = true; break; }
;                 __builtin_amdgcn_s_sleep(2);
;             }
;             __builtin_amdgcn_fence(__ATOMIC_ACQUIRE, "agent");
.LBB0_963:
	s_andn2_b64 vcc, exec, s[36:37]
	s_cbranch_vccz .LBB0_969
	s_waitcnt lgkmcnt(0)
	s_and_saveexec_b64 s[24:25], s[6:7]
	s_xor_b64 s[6:7], exec, s[24:25]
	s_cbranch_execz .LBB0_966
	s_nop 0

;     __device__ __forceinline__ bool run(const f32x4 (&v)[2][2][4][2], const Unit& u, int wr, int wc, int fr, int fq, PG8_LAS unsigned char* lds, int wid, int lane) const {
;     ...
;             __builtin_amdgcn_fence(__ATOMIC_ACQUIRE, "agent");
;             if (lane == 0) flag[0] = dead ? 1u : 0u;
;         }
;         asm volatile("s_waitcnt vmcnt(0) lgkmcnt(0)" ::: "memory"); __builtin_amdgcn_s_barrier(); asm volatile("" ::: "memory");
.LBB0_970:
	s_waitcnt vmcnt(0)
	s_nop 0
	s_and_b64 exec, exec, s[4:5]
	s_cbranch_execz .LBB0_972
	v_readlane_b32 s4, v254, 4
	v_cndmask_b32_e64 v162, 0, 1, s[22:23]
	s_nop 0
	v_mov_b32_e32 v163, s4
	ds_write_b32 v163, v162
